# v031 with 40 bytes of unreachable padding before the Fourier-2 setup (placement scan)
# speedup vs baseline: 1.0052x; 1.0052x over previous
.LBB0_713:
	s_andn2_b64 vcc, exec, s[76:77]
	s_waitcnt vmcnt(0) lgkmcnt(0)
	s_barrier
	s_cbranch_vccnz .LBB0_656
	ds_read2st64_b32 v[66:67], v64 offset1:1
	ds_read2st64_b32 v[76:77], v64 offset0:2 offset1:3
	ds_read2st64_b32 v[78:79], v64 offset0:4 offset1:5
	ds_read2st64_b32 v[80:81], v64 offset0:6 offset1:7
	ds_read2st64_b32 v[82:83], v64 offset0:8 offset1:9
	ds_read2st64_b32 v[84:85], v64 offset0:10 offset1:11
	ds_read2st64_b32 v[86:87], v64 offset0:12 offset1:13
	ds_read2st64_b32 v[88:89], v64 offset0:14 offset1:15
	ds_read2st64_b32 v[90:91], v64 offset0:16 offset1:17
	ds_read2st64_b32 v[116:117], v64 offset0:18 offset1:19
	ds_read2st64_b32 v[118:119], v64 offset0:20 offset1:21
	ds_read2st64_b32 v[120:121], v64 offset0:22 offset1:23
	ds_read2st64_b32 v[122:123], v64 offset0:24 offset1:25
	ds_read2st64_b32 v[124:125], v64 offset0:26 offset1:27
	ds_read2st64_b32 v[126:127], v64 offset0:28 offset1:29
	ds_read2st64_b32 v[128:129], v64 offset0:30 offset1:31
	ds_read2st64_b32 v[130:131], v64 offset0:32 offset1:33
	ds_read2st64_b32 v[132:133], v64 offset0:34 offset1:35
	ds_read2st64_b32 v[134:135], v64 offset0:36 offset1:37
	ds_read2st64_b32 v[136:137], v64 offset0:38 offset1:39
	ds_read2st64_b32 v[138:139], v64 offset0:40 offset1:41
	ds_read2st64_b32 v[140:141], v64 offset0:42 offset1:43
	ds_read2st64_b32 v[142:143], v64 offset0:44 offset1:45
	ds_read2st64_b32 v[148:149], v64 offset0:46 offset1:47
	ds_read2st64_b32 v[68:69], v64 offset0:58 offset1:59
	ds_read2st64_b32 v[150:151], v64 offset0:48 offset1:49
	ds_read2st64_b32 v[152:153], v64 offset0:50 offset1:51
	ds_read2st64_b32 v[154:155], v64 offset0:52 offset1:53
	ds_read2st64_b32 v[156:157], v64 offset0:54 offset1:55
	ds_read2st64_b32 v[72:73], v64 offset0:60 offset1:61
	ds_read2st64_b32 v[96:97], v64 offset0:62 offset1:63
	ds_read2st64_b32 v[162:163], v64 offset0:56 offset1:57
	s_waitcnt lgkmcnt(14)
	v_pk_fma_f32 v[98:99], v[50:51], v[74:75], v[76:77] op_sel_hi:[1,0,1] neg_lo:[0,0,1] neg_hi:[0,0,1]
	v_pk_fma_f32 v[104:105], v[48:49], v[74:75], v[66:67] op_sel_hi:[1,0,1] neg_lo:[0,0,1] neg_hi:[0,0,1]
	global_load_dwordx4 v[64:67], v146, s[30:31]
	global_load_dwordx4 v[48:51], v146, s[30:31] offset:32
	v_pk_mul_f32 v[164:165], v[104:105], v[104:105]
	s_waitcnt lgkmcnt(7)
	v_pk_fma_f32 v[70:71], v[26:27], v[74:75], v[68:69] op_sel_hi:[1,0,1] neg_lo:[0,0,1] neg_hi:[0,0,1]
	s_waitcnt lgkmcnt(2)
	v_pk_fma_f32 v[68:69], v[28:29], v[74:75], v[72:73] op_sel_hi:[1,0,1] neg_lo:[0,0,1] neg_hi:[0,0,1]
	s_waitcnt lgkmcnt(1)
	v_pk_fma_f32 v[72:73], v[30:31], v[74:75], v[96:97] op_sel_hi:[1,0,1] neg_lo:[0,0,1] neg_hi:[0,0,1]
	v_or_b32_e32 v26, s34, v161
	v_pk_mul_f32 v[160:161], v[98:99], v[98:99]
	v_pk_fma_f32 v[102:103], v[54:55], v[74:75], v[80:81] op_sel_hi:[1,0,1] neg_lo:[0,0,1] neg_hi:[0,0,1]
	v_pk_fma_f32 v[108:109], v[52:53], v[74:75], v[78:79] op_sel_hi:[1,0,1] neg_lo:[0,0,1] neg_hi:[0,0,1]
	v_pk_fma_f32 v[106:107], v[58:59], v[74:75], v[84:85] op_sel_hi:[1,0,1] neg_lo:[0,0,1] neg_hi:[0,0,1]
	v_pk_fma_f32 v[112:113], v[56:57], v[74:75], v[82:83] op_sel_hi:[1,0,1] neg_lo:[0,0,1] neg_hi:[0,0,1]
	v_pk_fma_f32 v[110:111], v[62:63], v[74:75], v[88:89] op_sel_hi:[1,0,1] neg_lo:[0,0,1] neg_hi:[0,0,1]
	v_pk_fma_f32 v[114:115], v[60:61], v[74:75], v[86:87] op_sel_hi:[1,0,1] neg_lo:[0,0,1] neg_hi:[0,0,1]
	v_pk_fma_f32 v[60:61], v[2:3], v[74:75], v[116:117] op_sel_hi:[1,0,1] neg_lo:[0,0,1] neg_hi:[0,0,1]
	v_pk_fma_f32 v[62:63], v[0:1], v[74:75], v[90:91] op_sel_hi:[1,0,1] neg_lo:[0,0,1] neg_hi:[0,0,1]
	v_pk_fma_f32 v[76:77], v[6:7], v[74:75], v[120:121] op_sel_hi:[1,0,1] neg_lo:[0,0,1] neg_hi:[0,0,1]
	v_pk_fma_f32 v[80:81], v[4:5], v[74:75], v[118:119] op_sel_hi:[1,0,1] neg_lo:[0,0,1] neg_hi:[0,0,1]
	v_pk_fma_f32 v[78:79], v[10:11], v[74:75], v[124:125] op_sel_hi:[1,0,1] neg_lo:[0,0,1] neg_hi:[0,0,1]
	v_pk_fma_f32 v[82:83], v[8:9], v[74:75], v[122:123] op_sel_hi:[1,0,1] neg_lo:[0,0,1] neg_hi:[0,0,1]
	v_pk_fma_f32 v[84:85], v[14:15], v[74:75], v[128:129] op_sel_hi:[1,0,1] neg_lo:[0,0,1] neg_hi:[0,0,1]
	v_pk_fma_f32 v[86:87], v[12:13], v[74:75], v[126:127] op_sel_hi:[1,0,1] neg_lo:[0,0,1] neg_hi:[0,0,1]
	v_pk_fma_f32 v[34:35], v[34:35], v[74:75], v[132:133] op_sel_hi:[1,0,1] neg_lo:[0,0,1] neg_hi:[0,0,1]
	v_pk_fma_f32 v[88:89], v[32:33], v[74:75], v[130:131] op_sel_hi:[1,0,1] neg_lo:[0,0,1] neg_hi:[0,0,1]
	v_pk_fma_f32 v[38:39], v[38:39], v[74:75], v[136:137] op_sel_hi:[1,0,1] neg_lo:[0,0,1] neg_hi:[0,0,1]
	v_pk_fma_f32 v[90:91], v[36:37], v[74:75], v[134:135] op_sel_hi:[1,0,1] neg_lo:[0,0,1] neg_hi:[0,0,1]
	v_pk_fma_f32 v[36:37], v[42:43], v[74:75], v[140:141] op_sel_hi:[1,0,1] neg_lo:[0,0,1] neg_hi:[0,0,1]
	v_pk_fma_f32 v[42:43], v[40:41], v[74:75], v[138:139] op_sel_hi:[1,0,1] neg_lo:[0,0,1] neg_hi:[0,0,1]
	v_pk_fma_f32 v[40:41], v[46:47], v[74:75], v[148:149] op_sel_hi:[1,0,1] neg_lo:[0,0,1] neg_hi:[0,0,1]
	v_pk_fma_f32 v[44:45], v[44:45], v[74:75], v[142:143] op_sel_hi:[1,0,1] neg_lo:[0,0,1] neg_hi:[0,0,1]
	v_pk_fma_f32 v[18:19], v[18:19], v[74:75], v[152:153] op_sel_hi:[1,0,1] neg_lo:[0,0,1] neg_hi:[0,0,1]
	v_pk_fma_f32 v[46:47], v[16:17], v[74:75], v[150:151] op_sel_hi:[1,0,1] neg_lo:[0,0,1] neg_hi:[0,0,1]
	v_pk_fma_f32 v[16:17], v[22:23], v[74:75], v[156:157] op_sel_hi:[1,0,1] neg_lo:[0,0,1] neg_hi:[0,0,1]
	v_pk_fma_f32 v[20:21], v[20:21], v[74:75], v[154:155] op_sel_hi:[1,0,1] neg_lo:[0,0,1] neg_hi:[0,0,1]
	s_waitcnt lgkmcnt(0)
	v_pk_fma_f32 v[22:23], v[24:25], v[74:75], v[162:163] op_sel_hi:[1,0,1] neg_lo:[0,0,1] neg_hi:[0,0,1]
	v_add_f32_e32 v74, v164, v165
	v_add_f32_e32 v74, v74, v160
	v_pk_mul_f32 v[168:169], v[108:109], v[108:109]
	v_add_f32_e32 v74, v74, v161
	v_add_f32_e32 v74, v74, v168
	v_pk_mul_f32 v[166:167], v[102:103], v[102:103]
	v_add_f32_e32 v74, v74, v169
	global_load_dwordx4 v[56:59], v146, s[30:31] offset:64
	global_load_dwordx4 v[52:55], v146, s[30:31] offset:96
	v_add_f32_e32 v74, v74, v166
	v_pk_mul_f32 v[172:173], v[112:113], v[112:113]
	v_add_f32_e32 v74, v74, v167
	v_add_f32_e32 v74, v74, v172
	v_pk_mul_f32 v[170:171], v[106:107], v[106:107]
	v_add_f32_e32 v74, v74, v173
	v_add_f32_e32 v74, v74, v170
	v_pk_mul_f32 v[178:179], v[114:115], v[114:115]
	v_add_f32_e32 v74, v74, v171
	v_add_f32_e32 v74, v74, v178
	v_pk_mul_f32 v[174:175], v[110:111], v[110:111]
	v_add_f32_e32 v74, v74, v179
	v_add_f32_e32 v74, v74, v174
	v_pk_mul_f32 v[180:181], v[62:63], v[62:63]
	v_add_f32_e32 v74, v74, v175
	v_add_f32_e32 v74, v74, v180
	v_pk_mul_f32 v[116:117], v[60:61], v[60:61]
	v_add_f32_e32 v74, v74, v181
	v_add_f32_e32 v74, v74, v116
	v_pk_mul_f32 v[118:119], v[80:81], v[80:81]
	v_add_f32_e32 v74, v74, v117
	v_add_f32_e32 v74, v74, v118
	v_pk_mul_f32 v[120:121], v[76:77], v[76:77]
	v_add_f32_e32 v74, v74, v119
	v_add_f32_e32 v74, v74, v120
	v_pk_mul_f32 v[122:123], v[82:83], v[82:83]
	v_add_f32_e32 v74, v74, v121
	v_add_f32_e32 v74, v74, v122
	v_pk_mul_f32 v[124:125], v[78:79], v[78:79]
	v_add_f32_e32 v74, v74, v123
	v_add_f32_e32 v74, v74, v124
	v_pk_mul_f32 v[126:127], v[86:87], v[86:87]
	v_add_f32_e32 v74, v74, v125
	v_add_f32_e32 v74, v74, v126
	v_pk_mul_f32 v[128:129], v[84:85], v[84:85]
	v_add_f32_e32 v74, v74, v127
	v_add_f32_e32 v74, v74, v128
	v_pk_mul_f32 v[130:131], v[88:89], v[88:89]
	v_add_f32_e32 v74, v74, v129
	v_add_f32_e32 v74, v74, v130
	v_pk_mul_f32 v[132:133], v[34:35], v[34:35]
	v_add_f32_e32 v74, v74, v131
	v_add_f32_e32 v74, v74, v132
	v_pk_mul_f32 v[134:135], v[90:91], v[90:91]
	v_add_f32_e32 v74, v74, v133
	v_add_f32_e32 v74, v74, v134
	v_pk_mul_f32 v[136:137], v[38:39], v[38:39]
	v_add_f32_e32 v74, v74, v135
	v_add_f32_e32 v74, v74, v136
	v_pk_mul_f32 v[138:139], v[42:43], v[42:43]
	v_add_f32_e32 v74, v74, v137
	v_add_f32_e32 v74, v74, v138
	v_pk_mul_f32 v[140:141], v[36:37], v[36:37]
	v_add_f32_e32 v74, v74, v139
	v_add_f32_e32 v74, v74, v140
	v_pk_mul_f32 v[142:143], v[44:45], v[44:45]
	v_add_f32_e32 v74, v74, v141
	v_add_f32_e32 v74, v74, v142
	v_pk_mul_f32 v[148:149], v[40:41], v[40:41]
	v_add_f32_e32 v74, v74, v143
	v_add_f32_e32 v74, v74, v148
	v_pk_mul_f32 v[150:151], v[46:47], v[46:47]
	v_add_f32_e32 v74, v74, v149
	v_add_f32_e32 v74, v74, v150
	v_pk_mul_f32 v[152:153], v[18:19], v[18:19]
	v_add_f32_e32 v74, v74, v151
	v_add_f32_e32 v74, v74, v152
	v_pk_mul_f32 v[154:155], v[20:21], v[20:21]
	v_add_f32_e32 v74, v74, v153
	v_add_f32_e32 v74, v74, v154
	v_pk_mul_f32 v[156:157], v[16:17], v[16:17]
	v_add_f32_e32 v74, v74, v155
	v_ashrrev_i32_e32 v27, 31, v26
	v_readlane_b32 s0, v255, 20
	v_add_f32_e32 v74, v74, v156
	v_lshlrev_b64 v[26:27], 12, v[26:27]
	v_readlane_b32 s1, v255, 21
	v_pk_mul_f32 v[24:25], v[22:23], v[22:23]
	v_add_f32_e32 v74, v74, v157
	v_lshl_add_u64 v[26:27], s[0:1], 0, v[26:27]
	v_add_f32_e32 v24, v74, v24
	v_pk_mul_f32 v[92:93], v[70:71], v[70:71]
	v_lshl_add_u64 v[100:101], v[26:27], 0, s[72:73]
	global_load_dwordx4 v[26:29], v146, s[30:31] offset:128
	global_load_dwordx4 v[0:3], v146, s[30:31] offset:160
	v_add_f32_e32 v24, v24, v25
	v_add_f32_e32 v24, v24, v92
	v_pk_mul_f32 v[94:95], v[68:69], v[68:69]
	v_add_f32_e32 v24, v24, v93
	v_add_f32_e32 v24, v24, v94
	v_pk_mul_f32 v[96:97], v[72:73], v[72:73]
	v_add_f32_e32 v24, v24, v95
	v_add_f32_e32 v24, v24, v96
	v_add_f32_e32 v74, v24, v97
	ds_bpermute_b32 v75, v75, v74
	global_load_dwordx4 v[8:11], v146, s[30:31] offset:192
	global_load_dwordx4 v[4:7], v146, s[30:31] offset:224
	global_load_dwordx4 v[30:33], v146, s[30:31] offset:256
	global_load_dwordx4 v[12:15], v146, s[30:31] offset:288
	global_load_dwordx4 v[92:95], v146, s[30:31] offset:320
	global_load_dwordx4 v[116:119], v146, s[30:31] offset:352
	v_lshlrev_b32_e32 v176, 3, v158
	s_waitcnt lgkmcnt(0)
	v_add_f32_e32 v74, v74, v75
	v_fmamk_f32 v74, v74, 0x3c000000, v213
	v_rsq_f32_e32 v74, v74
	v_lshl_add_u64 v[24:25], v[100:101], 0, v[176:177]
	global_load_dwordx4 v[120:123], v146, s[30:31] offset:384
	global_load_dwordx4 v[124:127], v146, s[30:31] offset:416
	global_load_dwordx4 v[128:131], v146, s[30:31] offset:448
	v_mul_f32_e32 v74, v145, v74
	v_pk_mul_f32 v[96:97], v[104:105], v[74:75] op_sel_hi:[1,0]
	s_waitcnt vmcnt(14)
	v_pk_mul_f32 v[64:65], v[64:65], v[96:97]
	v_pk_mul_f32 v[96:97], v[98:99], v[74:75] op_sel_hi:[1,0]
	v_cvt_pk_bf16_f32 v64, v64, v65
	v_pk_mul_f32 v[66:67], v[66:67], v[96:97]
	s_nop 0
	v_cvt_pk_bf16_f32 v65, v66, v67
	global_store_dwordx2 v[24:25], v[64:65], off
	v_pk_mul_f32 v[64:65], v[108:109], v[74:75] op_sel_hi:[1,0]
	s_waitcnt vmcnt(14)
	v_pk_mul_f32 v[48:49], v[48:49], v[64:65]
	v_pk_mul_f32 v[64:65], v[102:103], v[74:75] op_sel_hi:[1,0]
	v_cvt_pk_bf16_f32 v48, v48, v49
	v_pk_mul_f32 v[50:51], v[50:51], v[64:65]
	s_nop 0
	v_cvt_pk_bf16_f32 v49, v50, v51
	global_store_dwordx2 v[24:25], v[48:49], off offset:16
	v_pk_mul_f32 v[48:49], v[112:113], v[74:75] op_sel_hi:[1,0]
	v_pk_mul_f32 v[50:51], v[106:107], v[74:75] op_sel_hi:[1,0]
	s_waitcnt vmcnt(14)
	v_pk_mul_f32 v[48:49], v[56:57], v[48:49]
	v_pk_mul_f32 v[50:51], v[58:59], v[50:51]
	v_cvt_pk_bf16_f32 v48, v48, v49
	v_cvt_pk_bf16_f32 v49, v50, v51
	global_store_dwordx2 v[24:25], v[48:49], off offset:32
	v_pk_mul_f32 v[48:49], v[114:115], v[74:75] op_sel_hi:[1,0]
	s_waitcnt vmcnt(14)
	v_pk_mul_f32 v[48:49], v[52:53], v[48:49]
	s_nop 0
	v_cvt_pk_bf16_f32 v52, v48, v49
	v_pk_mul_f32 v[48:49], v[110:111], v[74:75] op_sel_hi:[1,0]
	s_nop 0
	v_pk_mul_f32 v[48:49], v[54:55], v[48:49]
	s_nop 0
	v_cvt_pk_bf16_f32 v53, v48, v49
	global_load_dwordx4 v[48:51], v146, s[30:31] offset:480
	s_nop 0
	global_store_dwordx2 v[24:25], v[52:53], off offset:48
	v_pk_mul_f32 v[52:53], v[62:63], v[74:75] op_sel_hi:[1,0]
	s_waitcnt vmcnt(15)
	v_pk_mul_f32 v[26:27], v[52:53], v[26:27]
	v_pk_mul_f32 v[52:53], v[60:61], v[74:75] op_sel_hi:[1,0]
	v_cvt_pk_bf16_f32 v26, v26, v27
	v_pk_mul_f32 v[28:29], v[52:53], v[28:29]
	s_nop 0
	v_cvt_pk_bf16_f32 v27, v28, v29
	global_store_dwordx2 v[24:25], v[26:27], off offset:64
	v_pk_mul_f32 v[26:27], v[80:81], v[74:75] op_sel_hi:[1,0]
	s_waitcnt vmcnt(15)
	v_pk_mul_f32 v[0:1], v[26:27], v[0:1]
	v_pk_mul_f32 v[26:27], v[76:77], v[74:75] op_sel_hi:[1,0]
	v_cvt_pk_bf16_f32 v0, v0, v1
	v_pk_mul_f32 v[2:3], v[26:27], v[2:3]
	s_nop 0
	v_cvt_pk_bf16_f32 v1, v2, v3
	global_store_dwordx2 v[24:25], v[0:1], off offset:80
	v_pk_mul_f32 v[0:1], v[82:83], v[74:75] op_sel_hi:[1,0]
	v_pk_mul_f32 v[2:3], v[78:79], v[74:75] op_sel_hi:[1,0]
	s_waitcnt vmcnt(15)
	v_pk_mul_f32 v[0:1], v[0:1], v[8:9]
	v_pk_mul_f32 v[2:3], v[2:3], v[10:11]
	v_cvt_pk_bf16_f32 v0, v0, v1
	v_cvt_pk_bf16_f32 v1, v2, v3
	global_store_dwordx2 v[24:25], v[0:1], off offset:96
	v_pk_mul_f32 v[0:1], v[86:87], v[74:75] op_sel_hi:[1,0]
	v_pk_mul_f32 v[2:3], v[84:85], v[74:75] op_sel_hi:[1,0]
	s_waitcnt vmcnt(15)
	v_pk_mul_f32 v[0:1], v[0:1], v[4:5]
	v_pk_mul_f32 v[2:3], v[2:3], v[6:7]
	v_cvt_pk_bf16_f32 v0, v0, v1
	v_cvt_pk_bf16_f32 v1, v2, v3
	global_store_dwordx2 v[24:25], v[0:1], off offset:112
	v_pk_mul_f32 v[0:1], v[88:89], v[74:75] op_sel_hi:[1,0]
	v_pk_mul_f32 v[2:3], v[34:35], v[74:75] op_sel_hi:[1,0]
	s_waitcnt vmcnt(15)
	v_pk_mul_f32 v[0:1], v[0:1], v[30:31]
	v_pk_mul_f32 v[2:3], v[2:3], v[32:33]
	v_cvt_pk_bf16_f32 v0, v0, v1
	v_cvt_pk_bf16_f32 v1, v2, v3
	global_store_dwordx2 v[24:25], v[0:1], off offset:128
	v_pk_mul_f32 v[0:1], v[90:91], v[74:75] op_sel_hi:[1,0]
	v_pk_mul_f32 v[2:3], v[38:39], v[74:75] op_sel_hi:[1,0]
	s_waitcnt vmcnt(15)
	v_pk_mul_f32 v[0:1], v[0:1], v[12:13]
	v_pk_mul_f32 v[2:3], v[2:3], v[14:15]
	v_cvt_pk_bf16_f32 v0, v0, v1
	v_cvt_pk_bf16_f32 v1, v2, v3
	global_store_dwordx2 v[24:25], v[0:1], off offset:144
	v_pk_mul_f32 v[0:1], v[42:43], v[74:75] op_sel_hi:[1,0]
	v_pk_mul_f32 v[2:3], v[36:37], v[74:75] op_sel_hi:[1,0]
	s_waitcnt vmcnt(15)
	v_pk_mul_f32 v[0:1], v[0:1], v[92:93]
	v_pk_mul_f32 v[2:3], v[2:3], v[94:95]
	v_cvt_pk_bf16_f32 v0, v0, v1
	v_cvt_pk_bf16_f32 v1, v2, v3
	global_store_dwordx2 v[24:25], v[0:1], off offset:160
	v_pk_mul_f32 v[0:1], v[44:45], v[74:75] op_sel_hi:[1,0]
	v_pk_mul_f32 v[2:3], v[40:41], v[74:75] op_sel_hi:[1,0]
	s_waitcnt vmcnt(15)
	v_pk_mul_f32 v[0:1], v[0:1], v[116:117]
	v_pk_mul_f32 v[2:3], v[2:3], v[118:119]
	v_cvt_pk_bf16_f32 v0, v0, v1
	v_cvt_pk_bf16_f32 v1, v2, v3
	global_store_dwordx2 v[24:25], v[0:1], off offset:176
	v_pk_mul_f32 v[0:1], v[46:47], v[74:75] op_sel_hi:[1,0]
	v_pk_mul_f32 v[2:3], v[18:19], v[74:75] op_sel_hi:[1,0]
	s_waitcnt vmcnt(15)
	v_pk_mul_f32 v[0:1], v[0:1], v[120:121]
	v_pk_mul_f32 v[2:3], v[2:3], v[122:123]
	v_cvt_pk_bf16_f32 v0, v0, v1
	v_cvt_pk_bf16_f32 v1, v2, v3
	global_store_dwordx2 v[24:25], v[0:1], off offset:192
	v_pk_mul_f32 v[0:1], v[20:21], v[74:75] op_sel_hi:[1,0]
	v_pk_mul_f32 v[2:3], v[16:17], v[74:75] op_sel_hi:[1,0]
	s_waitcnt vmcnt(15)
	v_pk_mul_f32 v[0:1], v[0:1], v[124:125]
	v_pk_mul_f32 v[2:3], v[2:3], v[126:127]
	v_cvt_pk_bf16_f32 v0, v0, v1
	v_cvt_pk_bf16_f32 v1, v2, v3
	global_store_dwordx2 v[24:25], v[0:1], off offset:208
	v_pk_mul_f32 v[0:1], v[22:23], v[74:75] op_sel_hi:[1,0]
	v_pk_mul_f32 v[2:3], v[70:71], v[74:75] op_sel_hi:[1,0]
	s_waitcnt vmcnt(15)
	v_pk_mul_f32 v[0:1], v[0:1], v[128:129]
	v_pk_mul_f32 v[2:3], v[2:3], v[130:131]
	v_cvt_pk_bf16_f32 v0, v0, v1
	v_cvt_pk_bf16_f32 v1, v2, v3
	global_store_dwordx2 v[24:25], v[0:1], off offset:224
	v_pk_mul_f32 v[0:1], v[68:69], v[74:75] op_sel_hi:[1,0]
	v_pk_mul_f32 v[2:3], v[72:73], v[74:75] op_sel_hi:[1,0]
	s_waitcnt vmcnt(12)
	v_pk_mul_f32 v[0:1], v[0:1], v[48:49]
	v_pk_mul_f32 v[2:3], v[2:3], v[50:51]
	v_cvt_pk_bf16_f32 v0, v0, v1
	v_cvt_pk_bf16_f32 v1, v2, v3
	global_store_dwordx2 v[24:25], v[0:1], off offset:240
	s_branch .LBB0_656
	s_nop 0
	s_nop 0
	s_nop 0
	s_nop 0
	s_nop 0
	s_nop 0
	s_nop 0
	s_nop 0
	s_nop 0
	s_nop 0
